# v30 + attention loops: saddr-form K/V loads with SALU-advanced SGPR bases, loop-invariant LDS address adds hoisted (about 6 VALU + 2 s_nop fewer per step)
# baseline (speedup 1.0000x reference)
.LBB0_1038:
	s_or_b64 exec, exec, s[4:5]
	v_and_b32_e32 v0, 0x60, v26
	s_movk_i32 s4, 0x90
	v_lshlrev_b32_e32 v2, 3, v32
	v_mad_u32_u24 v207, v203, s4, 0
	v_mad_u64_u32 v[0:1], s[4:5], v28, s4, v[0:1]
	v_and_or_b32 v0, v2, 8, v0
	v_lshlrev_b32_e32 v1, 6, v203
	v_add_u32_e32 v208, 0, v0
	v_add3_u32 v204, v207, v1, v184
	v_add_u32_e32 v1, 0, v4
	v_add_u32_e32 v205, 0x9800, v208
	s_waitcnt vmcnt(3)
	ds_write_b128 v1, v[8:11] offset:13312
	s_waitcnt vmcnt(2)
	ds_write2_b64 v205, v[16:17], v[18:19] offset0:128 offset1:130
	s_waitcnt lgkmcnt(0)
	s_barrier
	ds_read_b128 v[0:3], v204
	ds_read_b128 v[4:7], v204 offset:32
	ds_read_b128 v[8:11], v204 offset:6656
	ds_read_b128 v[12:15], v204 offset:6688
	ds_read_b128 v[16:19], v204 offset:64
	ds_read_b128 v[28:31], v204 offset:96
	ds_read_b128 v[64:67], v204 offset:6720
	ds_read_b128 v[68:71], v204 offset:6752
	ds_read_b128 v[72:75], v204 offset:128
	ds_read_b128 v[76:79], v204 offset:160
	ds_read_b128 v[80:83], v204 offset:6784
	ds_read_b128 v[84:87], v204 offset:6816
	s_mov_b32 s91, 2
	s_lshl_b32 s87, s6, 2
	s_waitcnt lgkmcnt(11)
	v_mfma_f32_32x32x16_bf16 v[48:63], v[0:3], v[100:103], 0
	s_mov_b32 s79, 0
	s_waitcnt lgkmcnt(9)
	v_mfma_f32_32x32x16_bf16 v[32:47], v[8:11], v[100:103], 0
	v_mfma_f32_32x32x16_bf16 v[48:63], v[4:7], v[104:107], v[48:63]
	s_waitcnt lgkmcnt(8)
	v_mfma_f32_32x32x16_bf16 v[32:47], v[12:15], v[104:107], v[32:47]
	s_waitcnt lgkmcnt(7)
	v_mfma_f32_32x32x16_bf16 v[48:63], v[16:19], v[108:111], v[48:63]
	s_waitcnt lgkmcnt(5)
	v_mfma_f32_32x32x16_bf16 v[32:47], v[64:67], v[108:111], v[32:47]
	v_mfma_f32_32x32x16_bf16 v[48:63], v[28:31], v[112:115], v[48:63]
	s_waitcnt lgkmcnt(4)
	v_mfma_f32_32x32x16_bf16 v[32:47], v[68:71], v[112:115], v[32:47]
	s_waitcnt lgkmcnt(3)
	v_mfma_f32_32x32x16_bf16 v[48:63], v[72:75], v[116:119], v[48:63]
	s_waitcnt lgkmcnt(1)
	v_mfma_f32_32x32x16_bf16 v[32:47], v[80:83], v[116:119], v[32:47]
	v_mfma_f32_32x32x16_bf16 v[48:63], v[76:79], v[120:123], v[48:63]
	s_waitcnt lgkmcnt(0)
	v_mfma_f32_32x32x16_bf16 v[32:47], v[84:87], v[120:123], v[32:47]
	ds_read_b128 v[172:175], v204 offset:13312
	ds_read_b128 v[152:155], v204 offset:13344
	ds_read_b128 v[180:183], v204 offset:19968
	ds_read_b128 v[164:167], v204 offset:20000
	ds_read_b128 v[156:159], v204 offset:13376
	ds_read_b128 v[140:143], v204 offset:13408
	ds_read_b128 v[176:179], v204 offset:20032
	ds_read_b128 v[160:163], v204 offset:20064
	ds_read_b128 v[148:151], v204 offset:13440
	ds_read_b128 v[136:139], v204 offset:13472
	ds_read_b128 v[168:171], v204 offset:20096
	ds_read_b128 v[144:147], v204 offset:20128
	s_add_u32 s4, s60, 0x100
	v_lshl_add_u64 v[0:1], s[60:61], 0, v[24:25]
	v_mov_b32_e32 v27, v97
	s_addc_u32 s5, 0, 0
	v_lshl_add_u64 v[190:191], v[0:1], 0, v[26:27]
	v_lshl_add_u64 v[0:1], s[4:5], 0, v[24:25]
	v_mov_b32_e32 v199, 0
	v_lshl_add_u64 v[188:189], s[96:97], 0, v[20:21]
	v_lshl_add_u64 v[186:187], s[96:97], 0, v[22:23]
	v_lshl_add_u64 v[98:99], v[0:1], 0, v[26:27]
	s_add_u32 s98, s94, 0x12209000
	s_addc_u32 s99, s95, 0
	s_add_u32 s100, s94, 0x11200000
	s_addc_u32 s101, s95, 0

	v_add_u32_e32 v206, 0xc000, v208
	v_add_u32_e32 v198, v207, v184

	v_exp_f32_e32 v48, v48
	v_exp_f32_e32 v49, v49
	v_exp_f32_e32 v50, v50
	v_add_f32_e32 v195, v48, v49
	v_exp_f32_e32 v51, v51
	v_add_f32_e32 v195, v50, v195
	v_exp_f32_e32 v52, v52
	v_add_f32_e32 v195, v51, v195
	v_exp_f32_e32 v53, v53
	v_add_f32_e32 v195, v52, v195
	v_exp_f32_e32 v54, v54
	v_add_f32_e32 v195, v53, v195
	v_exp_f32_e32 v55, v55
	v_add_f32_e32 v195, v54, v195
	v_exp_f32_e32 v56, v56
	v_add_f32_e32 v195, v55, v195
	v_exp_f32_e32 v57, v57
	v_add_f32_e32 v195, v56, v195
	v_exp_f32_e32 v58, v58
	v_add_f32_e32 v195, v57, v195
	v_exp_f32_e32 v59, v59
	v_add_f32_e32 v195, v58, v195
	v_exp_f32_e32 v60, v60
	v_add_f32_e32 v195, v59, v195
	v_exp_f32_e32 v61, v61
	v_add_f32_e32 v195, v60, v195
	v_exp_f32_e32 v62, v62
	v_add_f32_e32 v195, v61, v195
	v_exp_f32_e32 v63, v63
	v_add_f32_e32 v195, v62, v195
	v_add_f32_e32 v195, v63, v195
	s_movk_i32 s93, 0xbf
	v_mov_b32_e32 v0, 0
	v_mov_b32_e32 v1, v199
	v_mov_b32_e32 v2, v199
	v_mov_b32_e32 v3, v199
	v_mov_b32_e32 v4, v199
	v_mov_b32_e32 v5, v199
	v_mov_b32_e32 v6, v199
	v_mov_b32_e32 v7, v199
	v_mov_b32_e32 v8, v199
	v_mov_b32_e32 v9, v199
	v_mov_b32_e32 v10, v199
	v_mov_b32_e32 v11, v199
	v_mov_b32_e32 v12, v199
	v_mov_b32_e32 v13, v199
	v_mov_b32_e32 v14, v199
	v_mov_b32_e32 v15, v199
	v_mov_b32_e32 v16, 0
	v_mov_b32_e32 v17, v199
	v_mov_b32_e32 v18, v199
	v_mov_b32_e32 v19, v199
	v_mov_b32_e32 v20, v199
	v_mov_b32_e32 v21, v199
	v_mov_b32_e32 v22, v199
	v_mov_b32_e32 v23, v199
	v_mov_b32_e32 v24, v199
	v_mov_b32_e32 v25, v199
	v_mov_b32_e32 v26, v199
	v_mov_b32_e32 v27, v199
	v_mov_b32_e32 v28, v199
	v_mov_b32_e32 v29, v199
	v_mov_b32_e32 v30, v199
	v_mov_b32_e32 v31, v199
.LBB0_1039:
	s_waitcnt lgkmcnt(11)
	v_mfma_f32_32x32x16_bf16 v[64:79], v[172:175], v[100:103], 0
	v_exp_f32_e32 v32, v32
	v_exp_f32_e32 v33, v33
	v_exp_f32_e32 v34, v34
	s_waitcnt lgkmcnt(9)
	v_mfma_f32_32x32x16_bf16 v[80:95], v[180:183], v[100:103], 0
	v_add_f32_e32 v251, v32, v33
	v_cvt_pk_bf16_f32 v48, v48, v49
	v_exp_f32_e32 v35, v35
	v_add_f32_e32 v251, v34, v251
	v_mfma_f32_32x32x16_bf16 v[64:79], v[152:155], v[104:107], v[64:79]
	v_exp_f32_e32 v36, v36
	v_add_f32_e32 v251, v35, v251
	v_cvt_pk_bf16_f32 v49, v50, v51
	v_exp_f32_e32 v37, v37
	s_waitcnt lgkmcnt(8)
	v_mfma_f32_32x32x16_bf16 v[80:95], v[164:167], v[104:107], v[80:95]
	v_add_f32_e32 v251, v36, v251
	v_exp_f32_e32 v38, v38
	v_add_f32_e32 v251, v37, v251
	v_cvt_pk_bf16_f32 v50, v52, v53
	s_waitcnt lgkmcnt(7)
	v_mfma_f32_32x32x16_bf16 v[64:79], v[156:159], v[108:111], v[64:79]
	v_exp_f32_e32 v39, v39
	v_add_f32_e32 v251, v38, v251
	v_exp_f32_e32 v40, v40
	s_mul_i32 s6, s91, 0x3400
	s_add_i32 s7, s6, 0

	v_add_u32_e32 v253, s7, v96
	s_waitcnt vmcnt(1)
	ds_write_b128 v253, v[128:131]
	s_and_saveexec_b64 s[4:5], s[2:3]
	v_add_u32_e32 v253, s7, v185
	ds_write_b128 v253, v[124:127]
	s_or_b64 exec, exec, s[4:5]

	global_load_dwordx4 v[128:131], v188, s[98:99]
	s_waitcnt vmcnt(1)
	ds_write2_b64 v206, v[132:133], v[134:135] offset1:2

	s_and_saveexec_b64 s[4:5], s[2:3]
	s_cbranch_execz .LatA_h0
	global_load_dwordx4 v[124:127], v186, s[98:99]
.LatA_h0:
	s_or_b64 exec, exec, s[4:5]
	global_load_dwordx4 v[132:135], v190, s[100:101] offset:256
	s_add_u32 s98, s98, 0x3000
	s_addc_u32 s99, s99, 0
	s_add_u32 s100, s100, 0x80
	s_addc_u32 s101, s101, 0

	s_waitcnt lgkmcnt(7)
	v_mfma_f32_32x32x16_bf16 v[80:95], v[176:179], v[108:111], v[80:95]
	v_add_f32_e32 v251, v39, v251
	v_cvt_pk_bf16_f32 v51, v54, v55
	v_exp_f32_e32 v41, v41
	v_add_f32_e32 v251, v40, v251
	v_mfma_f32_32x32x16_bf16 v[64:79], v[140:143], v[112:115], v[64:79]
	v_exp_f32_e32 v42, v42
	v_add_f32_e32 v251, v41, v251
	v_cvt_pk_bf16_f32 v52, v56, v57
	v_exp_f32_e32 v43, v43
	s_waitcnt lgkmcnt(6)
	v_mfma_f32_32x32x16_bf16 v[80:95], v[160:163], v[112:115], v[80:95]
	v_add_f32_e32 v251, v42, v251
	v_exp_f32_e32 v44, v44
	v_add_f32_e32 v251, v43, v251
	v_cvt_pk_bf16_f32 v53, v58, v59
	s_waitcnt lgkmcnt(5)
	v_mfma_f32_32x32x16_bf16 v[64:79], v[148:151], v[116:119], v[64:79]
	v_exp_f32_e32 v45, v45
	v_add_f32_e32 v251, v44, v251
	v_exp_f32_e32 v46, v46
	v_add_f32_e32 v251, v45, v251
	ds_read_b128 v[210:213], v198 offset:44544
	ds_read_b128 v[214:217], v198 offset:39936
	ds_read_b128 v[218:221], v198 offset:39968
	ds_read_b128 v[222:225], v198 offset:44576
	ds_read_b128 v[226:229], v198 offset:40000
	ds_read_b128 v[230:233], v198 offset:44608
	ds_read_b128 v[234:237], v198 offset:40032
	ds_read_b128 v[238:241], v198 offset:44640
	s_waitcnt lgkmcnt(11)
	v_mfma_f32_32x32x16_bf16 v[80:95], v[168:171], v[116:119], v[80:95]
	v_cvt_pk_bf16_f32 v54, v60, v61
	v_exp_f32_e32 v47, v47
	v_add_f32_e32 v251, v46, v251
	v_add_f32_e32 v251, v47, v251
	v_mfma_f32_32x32x16_bf16 v[64:79], v[136:139], v[120:123], v[64:79]
	v_cvt_pk_bf16_f32 v55, v62, v63
	v_cvt_pk_bf16_f32 v32, v32, v33
	v_cvt_pk_bf16_f32 v33, v34, v35
	v_cvt_pk_bf16_f32 v34, v36, v37
	v_cvt_pk_bf16_f32 v35, v38, v39
	v_cvt_pk_bf16_f32 v36, v40, v41
	s_waitcnt lgkmcnt(10)
	v_mfma_f32_32x32x16_bf16 v[80:95], v[144:147], v[120:123], v[80:95]
	v_cvt_pk_bf16_f32 v37, v42, v43
	v_cvt_pk_bf16_f32 v38, v44, v45
	v_cvt_pk_bf16_f32 v39, v46, v47
	v_add_f32_e32 v195, v195, v251
	v_add_f32_e32 v199, v199, v195
	s_waitcnt lgkmcnt(0)
	s_barrier

	v_add_u32_e32 v197, s6, v204
	s_setprio 1
	v_mfma_f32_32x32x16_bf16 v[0:15], v[48:51], v[210:213], v[0:15]
	ds_read_b128 v[172:175], v197
	ds_read_b128 v[152:155], v197 offset:32
	v_mfma_f32_32x32x16_bf16 v[0:15], v[52:55], v[222:225], v[0:15]
	ds_read_b128 v[180:183], v197 offset:6656
	ds_read_b128 v[164:167], v197 offset:6688
	v_mfma_f32_32x32x16_bf16 v[0:15], v[32:35], v[230:233], v[0:15]
	ds_read_b128 v[156:159], v197 offset:64
	ds_read_b128 v[140:143], v197 offset:96
	v_exp_f32_e32 v64, v64
	v_exp_f32_e32 v65, v65
	v_exp_f32_e32 v66, v66
	v_add_f32_e32 v195, v64, v65
	v_mfma_f32_32x32x16_bf16 v[0:15], v[36:39], v[238:241], v[0:15]
	s_setprio 0
	ds_read_b128 v[176:179], v197 offset:6720
	ds_read_b128 v[160:163], v197 offset:6752
	v_exp_f32_e32 v67, v67
	v_add_f32_e32 v195, v66, v195
	v_exp_f32_e32 v68, v68
	v_add_f32_e32 v195, v67, v195
	v_exp_f32_e32 v69, v69
	v_add_f32_e32 v195, v68, v195
	v_mfma_f32_32x32x16_bf16 v[16:31], v[48:51], v[214:217], v[16:31]
	ds_read_b128 v[148:151], v197 offset:128
	ds_read_b128 v[136:139], v197 offset:160
	v_exp_f32_e32 v70, v70
	v_add_f32_e32 v195, v69, v195
	v_exp_f32_e32 v71, v71
	v_add_f32_e32 v195, v70, v195
	v_exp_f32_e32 v72, v72
	v_mfma_f32_32x32x16_bf16 v[16:31], v[52:55], v[218:221], v[16:31]
	ds_read_b128 v[168:171], v197 offset:6784
	ds_read_b128 v[144:147], v197 offset:6816
	v_add_f32_e32 v195, v71, v195
	v_exp_f32_e32 v73, v73
	v_add_f32_e32 v195, v72, v195
	v_exp_f32_e32 v74, v74
	v_add_f32_e32 v195, v73, v195
	v_mfma_f32_32x32x16_bf16 v[16:31], v[32:35], v[226:229], v[16:31]
	v_exp_f32_e32 v75, v75
	v_add_f32_e32 v195, v74, v195
	v_exp_f32_e32 v76, v76
	v_add_f32_e32 v195, v75, v195
	v_exp_f32_e32 v77, v77
	v_mfma_f32_32x32x16_bf16 v[16:31], v[36:39], v[234:237], v[16:31]
	v_add_f32_e32 v195, v76, v195
	v_exp_f32_e32 v78, v78
	v_add_f32_e32 v195, v77, v195
	v_exp_f32_e32 v79, v79
	v_add_f32_e32 v195, v78, v195
	v_add_f32_e32 v195, v79, v195
	s_waitcnt lgkmcnt(11)
	v_mfma_f32_32x32x16_bf16 v[48:63], v[172:175], v[100:103], 0
	v_exp_f32_e32 v80, v80
	v_exp_f32_e32 v81, v81
	v_exp_f32_e32 v82, v82
	s_waitcnt lgkmcnt(9)
	v_mfma_f32_32x32x16_bf16 v[32:47], v[180:183], v[100:103], 0
	v_add_f32_e32 v251, v80, v81
	v_cvt_pk_bf16_f32 v64, v64, v65
	v_exp_f32_e32 v83, v83
	v_add_f32_e32 v251, v82, v251
	v_mfma_f32_32x32x16_bf16 v[48:63], v[152:155], v[104:107], v[48:63]
	v_exp_f32_e32 v84, v84
	v_add_f32_e32 v251, v83, v251
	v_cvt_pk_bf16_f32 v65, v66, v67
	v_exp_f32_e32 v85, v85
	s_waitcnt lgkmcnt(8)
	v_mfma_f32_32x32x16_bf16 v[32:47], v[164:167], v[104:107], v[32:47]
	v_add_f32_e32 v251, v84, v251
	v_exp_f32_e32 v86, v86
	v_add_f32_e32 v251, v85, v251
	v_cvt_pk_bf16_f32 v66, v68, v69
	s_waitcnt lgkmcnt(7)
	v_mfma_f32_32x32x16_bf16 v[48:63], v[156:159], v[108:111], v[48:63]
	v_exp_f32_e32 v87, v87
	v_add_f32_e32 v251, v86, v251
	v_exp_f32_e32 v88, v88
	s_add_i32 s4, s91, 1
	s_cmp_lg_u32 s91, 2
	s_cselect_b32 s74, s4, 0
	s_mul_i32 s6, s74, 0x3400
	s_add_i32 s7, s6, 0

	v_add_u32_e32 v253, s7, v96
	s_waitcnt vmcnt(1)
	ds_write_b128 v253, v[128:131]
	s_and_saveexec_b64 s[4:5], s[2:3]
	v_add_u32_e32 v253, s7, v185
	ds_write_b128 v253, v[124:127]
	s_or_b64 exec, exec, s[4:5]

	s_waitcnt vmcnt(0)
	ds_write2_b64 v205, v[132:133], v[134:135] offset0:128 offset1:130
	global_load_dwordx4 v[128:131], v188, s[98:99]

	s_and_saveexec_b64 s[4:5], s[2:3]
	s_cbranch_execz .LatA_h1
	global_load_dwordx4 v[124:127], v186, s[98:99]
.LatA_h1:
	s_or_b64 exec, exec, s[4:5]
	global_load_dwordx4 v[132:135], v190, s[100:101] offset:256
	s_add_u32 s98, s98, 0x3000
	s_addc_u32 s99, s99, 0
	s_add_u32 s100, s100, 0x80
	s_addc_u32 s101, s101, 0

	s_waitcnt lgkmcnt(7)
	v_mfma_f32_32x32x16_bf16 v[32:47], v[176:179], v[108:111], v[32:47]
	v_add_f32_e32 v251, v87, v251
	v_cvt_pk_bf16_f32 v67, v70, v71
	v_exp_f32_e32 v89, v89
	v_add_f32_e32 v251, v88, v251
	v_mfma_f32_32x32x16_bf16 v[48:63], v[140:143], v[112:115], v[48:63]
	v_exp_f32_e32 v90, v90
	v_add_f32_e32 v251, v89, v251
	v_cvt_pk_bf16_f32 v68, v72, v73
	v_exp_f32_e32 v91, v91
	s_waitcnt lgkmcnt(6)
	v_mfma_f32_32x32x16_bf16 v[32:47], v[160:163], v[112:115], v[32:47]
	v_add_f32_e32 v251, v90, v251
	v_exp_f32_e32 v92, v92
	v_add_f32_e32 v251, v91, v251
	v_cvt_pk_bf16_f32 v69, v74, v75
	s_waitcnt lgkmcnt(5)
	v_mfma_f32_32x32x16_bf16 v[48:63], v[148:151], v[116:119], v[48:63]
	v_exp_f32_e32 v93, v93
	v_add_f32_e32 v251, v92, v251
	v_exp_f32_e32 v94, v94
	v_add_f32_e32 v251, v93, v251
	ds_read_b128 v[210:213], v198 offset:53760
	ds_read_b128 v[214:217], v198 offset:49152
	ds_read_b128 v[218:221], v198 offset:49184
	ds_read_b128 v[222:225], v198 offset:53792
	ds_read_b128 v[226:229], v198 offset:49216
	ds_read_b128 v[230:233], v198 offset:53824
	ds_read_b128 v[234:237], v198 offset:49248
	ds_read_b128 v[238:241], v198 offset:53856
	s_waitcnt lgkmcnt(11)
	v_mfma_f32_32x32x16_bf16 v[32:47], v[168:171], v[116:119], v[32:47]
	v_cvt_pk_bf16_f32 v70, v76, v77
	v_exp_f32_e32 v95, v95
	v_add_f32_e32 v251, v94, v251
	v_add_f32_e32 v251, v95, v251
	v_mfma_f32_32x32x16_bf16 v[48:63], v[136:139], v[120:123], v[48:63]
	v_cvt_pk_bf16_f32 v71, v78, v79
	v_cvt_pk_bf16_f32 v80, v80, v81
	v_cvt_pk_bf16_f32 v81, v82, v83
	v_cvt_pk_bf16_f32 v82, v84, v85
	v_cvt_pk_bf16_f32 v83, v86, v87
	v_cvt_pk_bf16_f32 v84, v88, v89
	s_waitcnt lgkmcnt(10)
	v_mfma_f32_32x32x16_bf16 v[32:47], v[144:147], v[120:123], v[32:47]
	v_cvt_pk_bf16_f32 v85, v90, v91
	v_cvt_pk_bf16_f32 v86, v92, v93
	v_cvt_pk_bf16_f32 v87, v94, v95
	v_add_f32_e32 v195, v195, v251
	v_add_f32_e32 v199, v199, v195
	s_add_i32 s92, s79, 2
	s_waitcnt lgkmcnt(0)
	s_barrier

	s_cmp_ge_u32 s92, s87
	s_cbranch_scc1 .LatA_yplain

	v_add_u32_e32 v197, s6, v204
	s_setprio 1
	v_mfma_f32_32x32x16_bf16 v[0:15], v[64:67], v[210:213], v[0:15]
	ds_read_b128 v[172:175], v197
	ds_read_b128 v[152:155], v197 offset:32
	v_mfma_f32_32x32x16_bf16 v[0:15], v[68:71], v[222:225], v[0:15]
	ds_read_b128 v[180:183], v197 offset:6656
	ds_read_b128 v[164:167], v197 offset:6688
	v_mfma_f32_32x32x16_bf16 v[0:15], v[80:83], v[230:233], v[0:15]
	ds_read_b128 v[156:159], v197 offset:64
	ds_read_b128 v[140:143], v197 offset:96
	v_exp_f32_e32 v48, v48
	v_exp_f32_e32 v49, v49
	v_exp_f32_e32 v50, v50
	v_add_f32_e32 v195, v48, v49
	v_mfma_f32_32x32x16_bf16 v[0:15], v[84:87], v[238:241], v[0:15]
	s_setprio 0
	ds_read_b128 v[176:179], v197 offset:6720
	ds_read_b128 v[160:163], v197 offset:6752
	v_exp_f32_e32 v51, v51
	v_add_f32_e32 v195, v50, v195
	v_exp_f32_e32 v52, v52
	v_add_f32_e32 v195, v51, v195
	v_exp_f32_e32 v53, v53
	v_add_f32_e32 v195, v52, v195
	v_mfma_f32_32x32x16_bf16 v[16:31], v[64:67], v[214:217], v[16:31]
	ds_read_b128 v[148:151], v197 offset:128
	ds_read_b128 v[136:139], v197 offset:160
	v_exp_f32_e32 v54, v54
	v_add_f32_e32 v195, v53, v195
	v_exp_f32_e32 v55, v55
	v_add_f32_e32 v195, v54, v195
	v_exp_f32_e32 v56, v56
	v_mfma_f32_32x32x16_bf16 v[16:31], v[68:71], v[218:221], v[16:31]
	ds_read_b128 v[168:171], v197 offset:6784
	ds_read_b128 v[144:147], v197 offset:6816
	v_add_f32_e32 v195, v55, v195
	v_exp_f32_e32 v57, v57
	v_add_f32_e32 v195, v56, v195
	v_exp_f32_e32 v58, v58
	v_add_f32_e32 v195, v57, v195
	v_mfma_f32_32x32x16_bf16 v[16:31], v[80:83], v[226:229], v[16:31]
	v_exp_f32_e32 v59, v59
	v_add_f32_e32 v195, v58, v195
	v_exp_f32_e32 v60, v60
	v_add_f32_e32 v195, v59, v195
	v_exp_f32_e32 v61, v61
	v_mfma_f32_32x32x16_bf16 v[16:31], v[84:87], v[234:237], v[16:31]
	v_add_f32_e32 v195, v60, v195
	v_exp_f32_e32 v62, v62
	v_add_f32_e32 v195, v61, v195
	v_exp_f32_e32 v63, v63
	v_add_f32_e32 v195, v62, v195
	v_add_f32_e32 v195, v63, v195
	s_branch .LatA_ctl

.LatA_ctl:
	s_add_i32 s4, s74, 1
	s_cmp_lg_u32 s74, 2
	s_cselect_b32 s91, s4, 0
	s_add_i32 s4, s93, 0x80
	s_cmp_ge_u32 s92, s87
	v_lshl_add_u64 v[192:193], v[98:99], 0, s[66:67]
	s_cbranch_scc1 .LatA_exit
	v_mov_b64_e32 v[98:99], v[192:193]
	s_mov_b32 s93, s4
	s_mov_b32 s79, s92
	s_branch .LBB0_1039
.LatA_exit:
	s_sub_u32 s4, s98, s94
	s_sub_u32 s4, s4, 0x12209000
	s_mov_b32 s5, 0
	v_lshl_add_u64 v[188:189], s[4:5], 0, v[188:189]
	v_lshl_add_u64 v[186:187], s[4:5], 0, v[186:187]
	s_sub_u32 s4, s100, s94
	s_sub_u32 s4, s4, 0x11200000
	v_lshl_add_u64 v[190:191], s[4:5], 0, v[190:191]
	s_add_i32 s4, s93, 0x80
	s_branch .LBB0_1049


.LBB0_1103:
	s_or_b64 exec, exec, s[4:5]
	v_and_b32_e32 v2, 0x60, v190
	s_movk_i32 s4, 0x90
	v_lshlrev_b32_e32 v1, 3, v24
	v_mad_u32_u24 v208, v207, s4, 0
	v_mad_u64_u32 v[2:3], s[4:5], v20, s4, v[2:3]
	v_and_or_b32 v1, v1, 8, v2
	v_lshlrev_b32_e32 v2, 6, v207
	v_add_u32_e32 v210, 0, v1
	v_add3_u32 v209, v208, v2, v184
	v_add_u32_e32 v0, 0, v0
	v_add_u32_e32 v211, 0x9800, v210
	s_waitcnt vmcnt(3)
	ds_write_b128 v0, v[4:7] offset:13312
	s_waitcnt vmcnt(2)
	ds_write2_b64 v211, v[8:9], v[10:11] offset0:128 offset1:130
	s_waitcnt lgkmcnt(0)
	s_barrier
	ds_read_b128 v[0:3], v209
	ds_read_b128 v[4:7], v209 offset:32
	ds_read_b128 v[8:11], v209 offset:6656
	ds_read_b128 v[12:15], v209 offset:6688
	ds_read_b128 v[16:19], v209 offset:64
	ds_read_b128 v[20:23], v209 offset:96
	ds_read_b128 v[24:27], v209 offset:6720
	ds_read_b128 v[28:31], v209 offset:6752
	ds_read_b128 v[64:67], v209 offset:128
	ds_read_b128 v[68:71], v209 offset:160
	ds_read_b128 v[72:75], v209 offset:6784
	ds_read_b128 v[76:79], v209 offset:6816
	s_mov_b32 s90, 2
	s_lshl_b32 s69, s68, 2
	s_mov_b32 s40, 0
	s_cmp_eq_u32 s68, 0
	s_waitcnt lgkmcnt(11)
	v_mfma_f32_32x32x16_bf16 v[48:63], v[0:3], v[100:103], 0
	s_waitcnt lgkmcnt(9)
	v_mfma_f32_32x32x16_bf16 v[32:47], v[8:11], v[100:103], 0
	v_mfma_f32_32x32x16_bf16 v[48:63], v[4:7], v[104:107], v[48:63]
	s_waitcnt lgkmcnt(8)
	v_mfma_f32_32x32x16_bf16 v[32:47], v[12:15], v[104:107], v[32:47]
	s_waitcnt lgkmcnt(7)
	v_mfma_f32_32x32x16_bf16 v[48:63], v[16:19], v[108:111], v[48:63]
	s_waitcnt lgkmcnt(5)
	v_mfma_f32_32x32x16_bf16 v[32:47], v[24:27], v[108:111], v[32:47]
	v_mfma_f32_32x32x16_bf16 v[48:63], v[20:23], v[112:115], v[48:63]
	s_waitcnt lgkmcnt(4)
	v_mfma_f32_32x32x16_bf16 v[32:47], v[28:31], v[112:115], v[32:47]
	s_waitcnt lgkmcnt(3)
	v_mfma_f32_32x32x16_bf16 v[48:63], v[64:67], v[116:119], v[48:63]
	s_waitcnt lgkmcnt(1)
	v_mfma_f32_32x32x16_bf16 v[32:47], v[72:75], v[116:119], v[32:47]
	v_mfma_f32_32x32x16_bf16 v[48:63], v[68:71], v[120:123], v[48:63]
	s_waitcnt lgkmcnt(0)
	v_mfma_f32_32x32x16_bf16 v[32:47], v[76:79], v[120:123], v[32:47]
	s_cbranch_scc1 .LBB0_1114
	ds_read_b128 v[172:175], v209 offset:13312
	ds_read_b128 v[152:155], v209 offset:13344
	ds_read_b128 v[180:183], v209 offset:19968
	ds_read_b128 v[164:167], v209 offset:20000
	ds_read_b128 v[156:159], v209 offset:13376
	ds_read_b128 v[140:143], v209 offset:13408
	ds_read_b128 v[176:179], v209 offset:20032
	ds_read_b128 v[160:163], v209 offset:20064
	ds_read_b128 v[148:151], v209 offset:13440
	ds_read_b128 v[136:139], v209 offset:13472
	ds_read_b128 v[168:171], v209 offset:20096
	ds_read_b128 v[144:147], v209 offset:20128
	v_lshl_add_u64 v[0:1], s[60:61], 0, v[192:193]
	v_mov_b32_e32 v191, v97
	v_mov_b32_e32 v198, 0
	v_lshl_add_u64 v[98:99], s[96:97], 0, v[186:187]
	v_lshl_add_u64 v[202:203], s[96:97], 0, v[188:189]
	v_lshl_add_u64 v[204:205], v[0:1], 0, v[190:191]
	s_add_u32 s98, s94, 0x12209000
	s_addc_u32 s99, s95, 0
	s_add_u32 s100, s94, 0x11200000
	s_addc_u32 s101, s95, 0

	v_add_u32_e32 v254, 0xc000, v210
	v_add_u32_e32 v196, v208, v184

	v_exp_f32_e32 v48, v48
	v_exp_f32_e32 v49, v49
	v_exp_f32_e32 v50, v50
	v_add_f32_e32 v195, v48, v49
	v_exp_f32_e32 v51, v51
	v_add_f32_e32 v195, v50, v195
	v_exp_f32_e32 v52, v52
	v_add_f32_e32 v195, v51, v195
	v_exp_f32_e32 v53, v53
	v_add_f32_e32 v195, v52, v195
	v_exp_f32_e32 v54, v54
	v_add_f32_e32 v195, v53, v195
	v_exp_f32_e32 v55, v55
	v_add_f32_e32 v195, v54, v195
	v_exp_f32_e32 v56, v56
	v_add_f32_e32 v195, v55, v195
	v_exp_f32_e32 v57, v57
	v_add_f32_e32 v195, v56, v195
	v_exp_f32_e32 v58, v58
	v_add_f32_e32 v195, v57, v195
	v_exp_f32_e32 v59, v59
	v_add_f32_e32 v195, v58, v195
	v_exp_f32_e32 v60, v60
	v_add_f32_e32 v195, v59, v195
	v_exp_f32_e32 v61, v61
	v_add_f32_e32 v195, v60, v195
	v_exp_f32_e32 v62, v62
	v_add_f32_e32 v195, v61, v195
	v_exp_f32_e32 v63, v63
	v_add_f32_e32 v195, v62, v195
	v_add_f32_e32 v195, v63, v195
	v_mov_b32_e32 v0, 0
	v_mov_b32_e32 v1, v198
	v_mov_b32_e32 v2, v198
	v_mov_b32_e32 v3, v198
	v_mov_b32_e32 v4, v198
	v_mov_b32_e32 v5, v198
	v_mov_b32_e32 v6, v198
	v_mov_b32_e32 v7, v198
	v_mov_b32_e32 v8, v198
	v_mov_b32_e32 v9, v198
	v_mov_b32_e32 v10, v198
	v_mov_b32_e32 v11, v198
	v_mov_b32_e32 v12, v198
	v_mov_b32_e32 v13, v198
	v_mov_b32_e32 v14, v198
	v_mov_b32_e32 v15, v198
	v_mov_b32_e32 v16, 0
	v_mov_b32_e32 v17, v198
	v_mov_b32_e32 v18, v198
	v_mov_b32_e32 v19, v198
	v_mov_b32_e32 v20, v198
	v_mov_b32_e32 v21, v198
	v_mov_b32_e32 v22, v198
	v_mov_b32_e32 v23, v198
	v_mov_b32_e32 v24, v198
	v_mov_b32_e32 v25, v198
	v_mov_b32_e32 v26, v198
	v_mov_b32_e32 v27, v198
	v_mov_b32_e32 v28, v198
	v_mov_b32_e32 v29, v198
	v_mov_b32_e32 v30, v198
	v_mov_b32_e32 v31, v198
	s_mov_b32 s41, 0x2c000
	s_branch .LBB0_1106
.LBB0_1106:
	s_waitcnt lgkmcnt(11)
	v_mfma_f32_32x32x16_bf16 v[64:79], v[172:175], v[100:103], 0
	v_exp_f32_e32 v32, v32
	v_exp_f32_e32 v33, v33
	v_exp_f32_e32 v34, v34
	s_waitcnt lgkmcnt(9)
	v_mfma_f32_32x32x16_bf16 v[80:95], v[180:183], v[100:103], 0
	v_add_f32_e32 v251, v32, v33
	v_cvt_pk_bf16_f32 v48, v48, v49
	v_exp_f32_e32 v35, v35
	v_add_f32_e32 v251, v34, v251
	v_mfma_f32_32x32x16_bf16 v[64:79], v[152:155], v[104:107], v[64:79]
	v_exp_f32_e32 v36, v36
	v_add_f32_e32 v251, v35, v251
	v_cvt_pk_bf16_f32 v49, v50, v51
	v_exp_f32_e32 v37, v37
	s_waitcnt lgkmcnt(8)
	v_mfma_f32_32x32x16_bf16 v[80:95], v[164:167], v[104:107], v[80:95]
	v_add_f32_e32 v251, v36, v251
	v_exp_f32_e32 v38, v38
	v_add_f32_e32 v251, v37, v251
	v_cvt_pk_bf16_f32 v50, v52, v53
	s_waitcnt lgkmcnt(7)
	v_mfma_f32_32x32x16_bf16 v[64:79], v[156:159], v[108:111], v[64:79]
	v_exp_f32_e32 v39, v39
	v_add_f32_e32 v251, v38, v251
	v_exp_f32_e32 v40, v40
	s_mul_i32 s6, s90, 0x3400
	s_add_i32 s7, s6, 0

	v_add_u32_e32 v253, s7, v96
	s_waitcnt vmcnt(1)
	ds_write_b128 v253, v[128:131]
	s_and_saveexec_b64 s[4:5], s[2:3]
	v_add_u32_e32 v253, s7, v185
	ds_write_b128 v253, v[124:127]
	s_or_b64 exec, exec, s[4:5]

	global_load_dwordx4 v[128:131], v98, s[98:99]
	s_waitcnt vmcnt(1)
	ds_write2_b64 v254, v[132:133], v[134:135] offset1:2

	s_and_saveexec_b64 s[4:5], s[2:3]
	s_cbranch_execz .LatB_h0
	global_load_dwordx4 v[124:127], v202, s[98:99]
.LatB_h0:
	s_or_b64 exec, exec, s[4:5]
	global_load_dwordx4 v[132:135], v204, s[100:101] offset:256
	s_add_u32 s98, s98, 0x3000
	s_addc_u32 s99, s99, 0
	s_add_u32 s100, s100, 0x80
	s_addc_u32 s101, s101, 0

	s_waitcnt lgkmcnt(7)
	v_mfma_f32_32x32x16_bf16 v[80:95], v[176:179], v[108:111], v[80:95]
	v_add_f32_e32 v251, v39, v251
	v_cvt_pk_bf16_f32 v51, v54, v55
	v_exp_f32_e32 v41, v41
	v_add_f32_e32 v251, v40, v251
	v_mfma_f32_32x32x16_bf16 v[64:79], v[140:143], v[112:115], v[64:79]
	v_exp_f32_e32 v42, v42
	v_add_f32_e32 v251, v41, v251
	v_cvt_pk_bf16_f32 v52, v56, v57
	v_exp_f32_e32 v43, v43
	s_waitcnt lgkmcnt(6)
	v_mfma_f32_32x32x16_bf16 v[80:95], v[160:163], v[112:115], v[80:95]
	v_add_f32_e32 v251, v42, v251
	v_exp_f32_e32 v44, v44
	v_add_f32_e32 v251, v43, v251
	v_cvt_pk_bf16_f32 v53, v58, v59
	s_waitcnt lgkmcnt(5)
	v_mfma_f32_32x32x16_bf16 v[64:79], v[148:151], v[116:119], v[64:79]
	v_exp_f32_e32 v45, v45
	v_add_f32_e32 v251, v44, v251
	v_exp_f32_e32 v46, v46
	v_add_f32_e32 v251, v45, v251
	ds_read_b128 v[212:215], v196 offset:44544
	ds_read_b128 v[216:219], v196 offset:39936
	ds_read_b128 v[220:223], v196 offset:39968
	ds_read_b128 v[224:227], v196 offset:44576
	ds_read_b128 v[228:231], v196 offset:40000
	ds_read_b128 v[232:235], v196 offset:44608
	ds_read_b128 v[236:239], v196 offset:40032
	ds_read_b128 v[240:243], v196 offset:44640
	s_waitcnt lgkmcnt(11)
	v_mfma_f32_32x32x16_bf16 v[80:95], v[168:171], v[116:119], v[80:95]
	v_cvt_pk_bf16_f32 v54, v60, v61
	v_exp_f32_e32 v47, v47
	v_add_f32_e32 v251, v46, v251
	v_add_f32_e32 v251, v47, v251
	v_mfma_f32_32x32x16_bf16 v[64:79], v[136:139], v[120:123], v[64:79]
	v_cvt_pk_bf16_f32 v55, v62, v63
	v_cvt_pk_bf16_f32 v32, v32, v33
	v_cvt_pk_bf16_f32 v33, v34, v35
	v_cvt_pk_bf16_f32 v34, v36, v37
	v_cvt_pk_bf16_f32 v35, v38, v39
	v_cvt_pk_bf16_f32 v36, v40, v41
	s_waitcnt lgkmcnt(10)
	v_mfma_f32_32x32x16_bf16 v[80:95], v[144:147], v[120:123], v[80:95]
	v_cvt_pk_bf16_f32 v37, v42, v43
	v_cvt_pk_bf16_f32 v38, v44, v45
	v_cvt_pk_bf16_f32 v39, v46, v47
	v_add_f32_e32 v195, v195, v251
	v_add_f32_e32 v198, v198, v195
	s_waitcnt lgkmcnt(0)
	s_barrier

	v_add_u32_e32 v197, s6, v209
	s_setprio 1
	v_mfma_f32_32x32x16_bf16 v[0:15], v[48:51], v[212:215], v[0:15]
	ds_read_b128 v[172:175], v197
	ds_read_b128 v[152:155], v197 offset:32
	v_mfma_f32_32x32x16_bf16 v[0:15], v[52:55], v[224:227], v[0:15]
	ds_read_b128 v[180:183], v197 offset:6656
	ds_read_b128 v[164:167], v197 offset:6688
	v_mfma_f32_32x32x16_bf16 v[0:15], v[32:35], v[232:235], v[0:15]
	ds_read_b128 v[156:159], v197 offset:64
	ds_read_b128 v[140:143], v197 offset:96
	v_exp_f32_e32 v64, v64
	v_exp_f32_e32 v65, v65
	v_exp_f32_e32 v66, v66
	v_add_f32_e32 v195, v64, v65
	v_mfma_f32_32x32x16_bf16 v[0:15], v[36:39], v[240:243], v[0:15]
	s_setprio 0
	ds_read_b128 v[176:179], v197 offset:6720
	ds_read_b128 v[160:163], v197 offset:6752
	v_exp_f32_e32 v67, v67
	v_add_f32_e32 v195, v66, v195
	v_exp_f32_e32 v68, v68
	v_add_f32_e32 v195, v67, v195
	v_exp_f32_e32 v69, v69
	v_add_f32_e32 v195, v68, v195
	v_mfma_f32_32x32x16_bf16 v[16:31], v[48:51], v[216:219], v[16:31]
	ds_read_b128 v[148:151], v197 offset:128
	ds_read_b128 v[136:139], v197 offset:160
	v_exp_f32_e32 v70, v70
	v_add_f32_e32 v195, v69, v195
	v_exp_f32_e32 v71, v71
	v_add_f32_e32 v195, v70, v195
	v_exp_f32_e32 v72, v72
	v_mfma_f32_32x32x16_bf16 v[16:31], v[52:55], v[220:223], v[16:31]
	ds_read_b128 v[168:171], v197 offset:6784
	ds_read_b128 v[144:147], v197 offset:6816
	v_add_f32_e32 v195, v71, v195
	v_exp_f32_e32 v73, v73
	v_add_f32_e32 v195, v72, v195
	v_exp_f32_e32 v74, v74
	v_add_f32_e32 v195, v73, v195
	v_mfma_f32_32x32x16_bf16 v[16:31], v[32:35], v[228:231], v[16:31]
	v_exp_f32_e32 v75, v75
	v_add_f32_e32 v195, v74, v195
	v_exp_f32_e32 v76, v76
	v_add_f32_e32 v195, v75, v195
	v_exp_f32_e32 v77, v77
	v_mfma_f32_32x32x16_bf16 v[16:31], v[36:39], v[236:239], v[16:31]
	v_add_f32_e32 v195, v76, v195
	v_exp_f32_e32 v78, v78
	v_add_f32_e32 v195, v77, v195
	v_exp_f32_e32 v79, v79
	v_add_f32_e32 v195, v78, v195
	v_add_f32_e32 v195, v79, v195
	s_waitcnt lgkmcnt(11)
	v_mfma_f32_32x32x16_bf16 v[48:63], v[172:175], v[100:103], 0
	v_exp_f32_e32 v80, v80
	v_exp_f32_e32 v81, v81
	v_exp_f32_e32 v82, v82
	s_waitcnt lgkmcnt(9)
	v_mfma_f32_32x32x16_bf16 v[32:47], v[180:183], v[100:103], 0
	v_add_f32_e32 v251, v80, v81
	v_cvt_pk_bf16_f32 v64, v64, v65
	v_exp_f32_e32 v83, v83
	v_add_f32_e32 v251, v82, v251
	v_mfma_f32_32x32x16_bf16 v[48:63], v[152:155], v[104:107], v[48:63]
	v_exp_f32_e32 v84, v84
	v_add_f32_e32 v251, v83, v251
	v_cvt_pk_bf16_f32 v65, v66, v67
	v_exp_f32_e32 v85, v85
	s_waitcnt lgkmcnt(8)
	v_mfma_f32_32x32x16_bf16 v[32:47], v[164:167], v[104:107], v[32:47]
	v_add_f32_e32 v251, v84, v251
	v_exp_f32_e32 v86, v86
	v_add_f32_e32 v251, v85, v251
	v_cvt_pk_bf16_f32 v66, v68, v69
	s_waitcnt lgkmcnt(7)
	v_mfma_f32_32x32x16_bf16 v[48:63], v[156:159], v[108:111], v[48:63]
	v_exp_f32_e32 v87, v87
	v_add_f32_e32 v251, v86, v251
	v_exp_f32_e32 v88, v88
	s_add_i32 s4, s90, 1
	s_cmp_lg_u32 s90, 2
	s_cselect_b32 s68, s4, 0
	s_mul_i32 s6, s68, 0x3400
	s_add_i32 s7, s6, 0

	v_add_u32_e32 v253, s7, v96
	s_waitcnt vmcnt(1)
	ds_write_b128 v253, v[128:131]
	s_and_saveexec_b64 s[4:5], s[2:3]
	v_add_u32_e32 v253, s7, v185
	ds_write_b128 v253, v[124:127]
	s_or_b64 exec, exec, s[4:5]

	s_waitcnt vmcnt(0)
	ds_write2_b64 v211, v[132:133], v[134:135] offset0:128 offset1:130
	global_load_dwordx4 v[128:131], v98, s[98:99]

	s_and_saveexec_b64 s[4:5], s[2:3]
	s_cbranch_execz .LatB_h1
	global_load_dwordx4 v[124:127], v202, s[98:99]
.LatB_h1:
	s_or_b64 exec, exec, s[4:5]
	global_load_dwordx4 v[132:135], v204, s[100:101] offset:256
	s_add_u32 s98, s98, 0x3000
	s_addc_u32 s99, s99, 0
	s_add_u32 s100, s100, 0x80
	s_addc_u32 s101, s101, 0

	s_waitcnt lgkmcnt(7)
	v_mfma_f32_32x32x16_bf16 v[32:47], v[176:179], v[108:111], v[32:47]
	v_add_f32_e32 v251, v87, v251
	v_cvt_pk_bf16_f32 v67, v70, v71
	v_exp_f32_e32 v89, v89
	v_add_f32_e32 v251, v88, v251
	v_mfma_f32_32x32x16_bf16 v[48:63], v[140:143], v[112:115], v[48:63]
	v_exp_f32_e32 v90, v90
	v_add_f32_e32 v251, v89, v251
	v_cvt_pk_bf16_f32 v68, v72, v73
	v_exp_f32_e32 v91, v91
	s_waitcnt lgkmcnt(6)
	v_mfma_f32_32x32x16_bf16 v[32:47], v[160:163], v[112:115], v[32:47]
	v_add_f32_e32 v251, v90, v251
	v_exp_f32_e32 v92, v92
	v_add_f32_e32 v251, v91, v251
	v_cvt_pk_bf16_f32 v69, v74, v75
	s_waitcnt lgkmcnt(5)
	v_mfma_f32_32x32x16_bf16 v[48:63], v[148:151], v[116:119], v[48:63]
	v_exp_f32_e32 v93, v93
	v_add_f32_e32 v251, v92, v251
	v_exp_f32_e32 v94, v94
	v_add_f32_e32 v251, v93, v251
	ds_read_b128 v[212:215], v196 offset:53760
	ds_read_b128 v[216:219], v196 offset:49152
	ds_read_b128 v[220:223], v196 offset:49184
	ds_read_b128 v[224:227], v196 offset:53792
	ds_read_b128 v[228:231], v196 offset:49216
	ds_read_b128 v[232:235], v196 offset:53824
	ds_read_b128 v[236:239], v196 offset:49248
	ds_read_b128 v[240:243], v196 offset:53856
	s_waitcnt lgkmcnt(11)
	v_mfma_f32_32x32x16_bf16 v[32:47], v[168:171], v[116:119], v[32:47]
	v_cvt_pk_bf16_f32 v70, v76, v77
	v_exp_f32_e32 v95, v95
	v_add_f32_e32 v251, v94, v251
	v_add_f32_e32 v251, v95, v251
	v_mfma_f32_32x32x16_bf16 v[48:63], v[136:139], v[120:123], v[48:63]
	v_cvt_pk_bf16_f32 v71, v78, v79
	v_cvt_pk_bf16_f32 v80, v80, v81
	v_cvt_pk_bf16_f32 v81, v82, v83
	v_cvt_pk_bf16_f32 v82, v84, v85
	v_cvt_pk_bf16_f32 v83, v86, v87
	v_cvt_pk_bf16_f32 v84, v88, v89
	s_waitcnt lgkmcnt(10)
	v_mfma_f32_32x32x16_bf16 v[32:47], v[144:147], v[120:123], v[32:47]
	v_cvt_pk_bf16_f32 v85, v90, v91
	v_cvt_pk_bf16_f32 v86, v92, v93
	v_cvt_pk_bf16_f32 v87, v94, v95
	v_add_f32_e32 v195, v195, v251
	v_add_f32_e32 v198, v198, v195
	s_add_i32 s40, s40, 2
	s_waitcnt lgkmcnt(0)
	s_barrier

	s_cmp_ge_u32 s40, s69
	s_cbranch_scc1 .LatB_yplain

	v_add_u32_e32 v197, s6, v209
	s_setprio 1
	v_mfma_f32_32x32x16_bf16 v[0:15], v[64:67], v[212:215], v[0:15]
	ds_read_b128 v[172:175], v197
	ds_read_b128 v[152:155], v197 offset:32
	v_mfma_f32_32x32x16_bf16 v[0:15], v[68:71], v[224:227], v[0:15]
	ds_read_b128 v[180:183], v197 offset:6656
	ds_read_b128 v[164:167], v197 offset:6688
	v_mfma_f32_32x32x16_bf16 v[0:15], v[80:83], v[232:235], v[0:15]
	ds_read_b128 v[156:159], v197 offset:64
	ds_read_b128 v[140:143], v197 offset:96
	v_exp_f32_e32 v48, v48
	v_exp_f32_e32 v49, v49
	v_exp_f32_e32 v50, v50
	v_add_f32_e32 v195, v48, v49
	v_mfma_f32_32x32x16_bf16 v[0:15], v[84:87], v[240:243], v[0:15]
	s_setprio 0
	ds_read_b128 v[176:179], v197 offset:6720
	ds_read_b128 v[160:163], v197 offset:6752
	v_exp_f32_e32 v51, v51
	v_add_f32_e32 v195, v50, v195
	v_exp_f32_e32 v52, v52
	v_add_f32_e32 v195, v51, v195
	v_exp_f32_e32 v53, v53
	v_add_f32_e32 v195, v52, v195
	v_mfma_f32_32x32x16_bf16 v[16:31], v[64:67], v[216:219], v[16:31]
	ds_read_b128 v[148:151], v197 offset:128
	ds_read_b128 v[136:139], v197 offset:160
	v_exp_f32_e32 v54, v54
	v_add_f32_e32 v195, v53, v195
	v_exp_f32_e32 v55, v55
	v_add_f32_e32 v195, v54, v195
	v_exp_f32_e32 v56, v56
	v_mfma_f32_32x32x16_bf16 v[16:31], v[68:71], v[220:223], v[16:31]
	ds_read_b128 v[168:171], v197 offset:6784
	ds_read_b128 v[144:147], v197 offset:6816
	v_add_f32_e32 v195, v55, v195
	v_exp_f32_e32 v57, v57
	v_add_f32_e32 v195, v56, v195
	v_exp_f32_e32 v58, v58
	v_add_f32_e32 v195, v57, v195
	v_mfma_f32_32x32x16_bf16 v[16:31], v[80:83], v[228:231], v[16:31]
	v_exp_f32_e32 v59, v59
	v_add_f32_e32 v195, v58, v195
	v_exp_f32_e32 v60, v60
	v_add_f32_e32 v195, v59, v195
	v_exp_f32_e32 v61, v61
	v_mfma_f32_32x32x16_bf16 v[16:31], v[84:87], v[236:239], v[16:31]
	v_add_f32_e32 v195, v60, v195
	v_exp_f32_e32 v62, v62
	v_add_f32_e32 v195, v61, v195
	v_exp_f32_e32 v63, v63
	v_add_f32_e32 v195, v62, v195
	v_add_f32_e32 v195, v63, v195
	s_branch .LatB_ctl

.LatB_ctl:
	s_add_i32 s4, s68, 1
	s_cmp_lg_u32 s68, 2
	s_cselect_b32 s90, s4, 0
	s_cmp_ge_u32 s40, s69
	s_cbranch_scc1 .LatB_exit
	s_branch .LBB0_1106
.LatB_exit:
	s_sub_u32 s4, s98, s94
	s_sub_u32 s4, s4, 0x12209000
	s_mov_b32 s5, 0
	v_lshl_add_u64 v[98:99], s[4:5], 0, v[98:99]
	v_lshl_add_u64 v[202:203], s[4:5], 0, v[202:203]
	s_sub_u32 s4, s100, s94
	s_sub_u32 s4, s4, 0x11200000
	v_lshl_add_u64 v[204:205], s[4:5], 0, v[204:205]
	s_add_i32 s4, s68, 1
	s_branch .LBB0_1115

